# attention unit epilogue: per-step sub-LN gain load to a free quad and both step loads issued before the previous step's store (counted waits no longer drain that store each step)
# baseline (speedup 1.0000x reference)
.LBB0_1151:
	s_andn2_b64 vcc, exec, s[4:5]
	s_waitcnt vmcnt(0) lgkmcnt(0)
	s_barrier
	s_cbranch_vccnz .LBB0_1153
	s_lshl_b32 s8, s35, 7
	s_and_b32 s8, s8, 0xf80
	s_add_i32 s8, s8, s18
	s_ashr_i32 s9, s8, 31
	v_lshl_add_u64 v[64:65], v[184:185], 0, s[8:9]
	v_lshlrev_b64 v[64:65], 11, v[64:65]
	v_lshl_add_u64 v[64:65], v[64:65], 0, s[52:53]
	v_lshlrev_b64 v[80:81], 1, v[64:65]
	v_lshl_add_u64 v[68:69], v[190:191], 0, v[80:81]
	global_load_dwordx2 v[98:99], v[68:69], off
	ds_read2st64_b32 v[70:71], v245 offset1:1
	ds_read2st64_b32 v[72:73], v245 offset0:2 offset1:3
	ds_read2st64_b32 v[76:77], v245 offset0:4 offset1:5
	ds_read2st64_b32 v[74:75], v245 offset0:6 offset1:7
	ds_read2st64_b32 v[126:127], v245 offset0:8 offset1:9
	ds_read2st64_b32 v[144:145], v245 offset0:10 offset1:11
	ds_read2st64_b32 v[146:147], v245 offset0:12 offset1:13
	ds_read2st64_b32 v[148:149], v245 offset0:14 offset1:15
	ds_read2st64_b32 v[150:151], v245 offset0:16 offset1:17
	ds_read2st64_b32 v[152:153], v245 offset0:18 offset1:19
	ds_read2st64_b32 v[124:125], v245 offset0:20 offset1:21
	ds_read2st64_b32 v[154:155], v245 offset0:22 offset1:23
	ds_read2st64_b32 v[120:121], v245 offset0:24 offset1:25
	ds_read2st64_b32 v[122:123], v245 offset0:26 offset1:27
	ds_read2st64_b32 v[116:117], v245 offset0:28 offset1:29
	ds_read2st64_b32 v[118:119], v245 offset0:30 offset1:31
	ds_read2st64_b32 v[110:111], v245 offset0:32 offset1:33
	ds_read2st64_b32 v[114:115], v245 offset0:34 offset1:35
	ds_read2st64_b32 v[104:105], v245 offset0:36 offset1:37
	ds_read2st64_b32 v[112:113], v245 offset0:38 offset1:39
	ds_read2st64_b32 v[96:97], v245 offset0:40 offset1:41
	ds_read2st64_b32 v[108:109], v245 offset0:42 offset1:43
	ds_read2st64_b32 v[92:93], v245 offset0:44 offset1:45
	ds_read2st64_b32 v[102:103], v245 offset0:46 offset1:47
	ds_read2st64_b32 v[86:87], v245 offset0:56 offset1:57
	ds_read2st64_b32 v[88:89], v245 offset0:58 offset1:59
	ds_read2st64_b32 v[82:83], v245 offset0:60 offset1:61
	ds_read2st64_b32 v[84:85], v245 offset0:62 offset1:63
	ds_read2st64_b32 v[94:95], v245 offset0:48 offset1:49
	ds_read2st64_b32 v[106:107], v245 offset0:50 offset1:51
	ds_read2st64_b32 v[90:91], v245 offset0:52 offset1:53
	ds_read2st64_b32 v[100:101], v245 offset0:54 offset1:55
	s_waitcnt lgkmcnt(4)
	v_pk_fma_f32 v[14:15], v[14:15], v[78:79], v[84:85] op_sel_hi:[1,0,1] neg_lo:[0,0,1] neg_hi:[0,0,1]
	v_pk_fma_f32 v[84:85], v[48:49], v[78:79], v[70:71] op_sel_hi:[1,0,1] neg_lo:[0,0,1] neg_hi:[0,0,1]
	v_pk_fma_f32 v[48:49], v[40:41], v[78:79], v[120:121] op_sel_hi:[1,0,1] neg_lo:[0,0,1] neg_hi:[0,0,1]
	v_pk_fma_f32 v[40:41], v[46:47], v[78:79], v[118:119] op_sel_hi:[1,0,1] neg_lo:[0,0,1] neg_hi:[0,0,1]
	v_pk_fma_f32 v[46:47], v[18:19], v[78:79], v[114:115] op_sel_hi:[1,0,1] neg_lo:[0,0,1] neg_hi:[0,0,1]
	v_pk_fma_f32 v[12:13], v[12:13], v[78:79], v[82:83] op_sel_hi:[1,0,1] neg_lo:[0,0,1] neg_hi:[0,0,1]
	v_pk_fma_f32 v[82:83], v[50:51], v[78:79], v[72:73] op_sel_hi:[1,0,1] neg_lo:[0,0,1] neg_hi:[0,0,1]
	v_pk_fma_f32 v[72:73], v[32:33], v[78:79], v[150:151] op_sel_hi:[1,0,1] neg_lo:[0,0,1] neg_hi:[0,0,1]
	v_pk_fma_f32 v[74:75], v[54:55], v[78:79], v[74:75] op_sel_hi:[1,0,1] neg_lo:[0,0,1] neg_hi:[0,0,1]
	v_pk_fma_f32 v[76:77], v[52:53], v[78:79], v[76:77] op_sel_hi:[1,0,1] neg_lo:[0,0,1] neg_hi:[0,0,1]
	v_pk_fma_f32 v[58:59], v[58:59], v[78:79], v[144:145] op_sel_hi:[1,0,1] neg_lo:[0,0,1] neg_hi:[0,0,1]
	v_pk_fma_f32 v[70:71], v[56:57], v[78:79], v[126:127] op_sel_hi:[1,0,1] neg_lo:[0,0,1] neg_hi:[0,0,1]
	v_pk_fma_f32 v[56:57], v[62:63], v[78:79], v[148:149] op_sel_hi:[1,0,1] neg_lo:[0,0,1] neg_hi:[0,0,1]
	v_pk_fma_f32 v[62:63], v[60:61], v[78:79], v[146:147] op_sel_hi:[1,0,1] neg_lo:[0,0,1] neg_hi:[0,0,1]
	v_pk_fma_f32 v[60:61], v[34:35], v[78:79], v[152:153] op_sel_hi:[1,0,1] neg_lo:[0,0,1] neg_hi:[0,0,1]
	v_pk_fma_f32 v[52:53], v[38:39], v[78:79], v[154:155] op_sel_hi:[1,0,1] neg_lo:[0,0,1] neg_hi:[0,0,1]
	v_pk_fma_f32 v[54:55], v[36:37], v[78:79], v[124:125] op_sel_hi:[1,0,1] neg_lo:[0,0,1] neg_hi:[0,0,1]
	v_pk_fma_f32 v[42:43], v[42:43], v[78:79], v[122:123] op_sel_hi:[1,0,1] neg_lo:[0,0,1] neg_hi:[0,0,1]
	v_pk_fma_f32 v[44:45], v[44:45], v[78:79], v[116:117] op_sel_hi:[1,0,1] neg_lo:[0,0,1] neg_hi:[0,0,1]
	v_pk_mul_f32 v[122:123], v[84:85], v[84:85]
	global_load_dwordx4 v[64:67], v[188:189], off
	v_pk_mul_f32 v[120:121], v[82:83], v[82:83]
	v_pk_mul_f32 v[126:127], v[76:77], v[76:77]
	v_pk_mul_f32 v[124:125], v[74:75], v[74:75]
	v_pk_mul_f32 v[146:147], v[70:71], v[70:71]
	v_pk_mul_f32 v[144:145], v[58:59], v[58:59]
	v_pk_mul_f32 v[150:151], v[62:63], v[62:63]
	v_pk_mul_f32 v[148:149], v[56:57], v[56:57]
	v_pk_mul_f32 v[154:155], v[72:73], v[72:73]
	v_pk_mul_f32 v[152:153], v[60:61], v[60:61]
	v_pk_mul_f32 v[158:159], v[54:55], v[54:55]
	v_pk_mul_f32 v[156:157], v[52:53], v[52:53]
	v_pk_mul_f32 v[162:163], v[48:49], v[48:49]
	v_pk_mul_f32 v[160:161], v[42:43], v[42:43]
	v_pk_mul_f32 v[166:167], v[44:45], v[44:45]
	v_pk_mul_f32 v[164:165], v[40:41], v[40:41]
	v_pk_mul_f32 v[172:173], v[46:47], v[46:47]
	v_pk_mul_f32 v[116:117], v[12:13], v[12:13]
	v_pk_mul_f32 v[118:119], v[14:15], v[14:15]
	global_load_dwordx2 v[114:115], v[68:69], off offset:16
	s_mov_b32 s8, 0x800000
	s_waitcnt vmcnt(2)
	v_lshlrev_b32_e32 v168, 16, v98
	v_and_b32_e32 v169, 0xffff0000, v98
	v_lshlrev_b32_e32 v98, 16, v99
	v_mul_f32_e32 v18, 0xbfb8aa3b, v168
	v_mul_f32_e32 v19, 0xbfb8aa3b, v169
	v_mul_f32_e32 v32, 0xbfb8aa3b, v98
	v_exp_f32_e32 v18, v18
	v_exp_f32_e32 v19, v19
	v_exp_f32_e32 v79, v32
	v_and_b32_e32 v99, 0xffff0000, v99
	v_mul_f32_e32 v33, 0xbfb8aa3b, v99
	v_add_f32_e32 v18, 1.0, v18
	v_add_f32_e32 v19, 1.0, v19
	v_exp_f32_e32 v174, v33
	v_rcp_f32_e32 v170, v18
	v_rcp_f32_e32 v171, v19
	v_pk_fma_f32 v[50:51], v[16:17], v[78:79], v[110:111] op_sel_hi:[1,0,1] neg_lo:[0,0,1] neg_hi:[0,0,1]
	v_pk_fma_f32 v[36:37], v[22:23], v[78:79], v[112:113] op_sel_hi:[1,0,1] neg_lo:[0,0,1] neg_hi:[0,0,1]
	v_pk_fma_f32 v[38:39], v[20:21], v[78:79], v[104:105] op_sel_hi:[1,0,1] neg_lo:[0,0,1] neg_hi:[0,0,1]
	v_pk_fma_f32 v[32:33], v[26:27], v[78:79], v[108:109] op_sel_hi:[1,0,1] neg_lo:[0,0,1] neg_hi:[0,0,1]
	v_pk_fma_f32 v[34:35], v[24:25], v[78:79], v[96:97] op_sel_hi:[1,0,1] neg_lo:[0,0,1] neg_hi:[0,0,1]
	v_pk_fma_f32 v[24:25], v[30:31], v[78:79], v[102:103] op_sel_hi:[1,0,1] neg_lo:[0,0,1] neg_hi:[0,0,1]
	v_pk_fma_f32 v[26:27], v[28:29], v[78:79], v[92:93] op_sel_hi:[1,0,1] neg_lo:[0,0,1] neg_hi:[0,0,1]
	s_waitcnt lgkmcnt(2)
	v_pk_fma_f32 v[20:21], v[2:3], v[78:79], v[106:107] op_sel_hi:[1,0,1] neg_lo:[0,0,1] neg_hi:[0,0,1]
	v_pk_fma_f32 v[22:23], v[0:1], v[78:79], v[94:95] op_sel_hi:[1,0,1] neg_lo:[0,0,1] neg_hi:[0,0,1]
	s_waitcnt lgkmcnt(0)
	v_pk_fma_f32 v[16:17], v[6:7], v[78:79], v[100:101] op_sel_hi:[1,0,1] neg_lo:[0,0,1] neg_hi:[0,0,1]
	v_pk_fma_f32 v[18:19], v[4:5], v[78:79], v[90:91] op_sel_hi:[1,0,1] neg_lo:[0,0,1] neg_hi:[0,0,1]
	v_pk_fma_f32 v[4:5], v[10:11], v[78:79], v[88:89] op_sel_hi:[1,0,1] neg_lo:[0,0,1] neg_hi:[0,0,1]
	v_pk_fma_f32 v[6:7], v[8:9], v[78:79], v[86:87] op_sel_hi:[1,0,1] neg_lo:[0,0,1] neg_hi:[0,0,1]
	v_add_f32_e32 v78, v122, v123
	v_add_f32_e32 v78, v78, v120
	v_add_f32_e32 v78, v78, v121
	v_add_f32_e32 v78, v78, v126
	v_add_f32_e32 v78, v78, v127
	v_add_f32_e32 v78, v78, v124
	v_add_f32_e32 v78, v78, v125
	v_add_f32_e32 v78, v78, v146
	v_add_f32_e32 v78, v78, v147
	v_add_f32_e32 v78, v78, v144
	v_add_f32_e32 v78, v78, v145
	v_add_f32_e32 v78, v78, v150
	v_add_f32_e32 v78, v78, v151
	v_add_f32_e32 v78, v78, v148
	v_add_f32_e32 v78, v78, v149
	v_add_f32_e32 v78, v78, v154
	v_add_f32_e32 v78, v78, v155
	v_add_f32_e32 v78, v78, v152
	v_add_f32_e32 v78, v78, v153
	v_add_f32_e32 v78, v78, v158
	v_add_f32_e32 v78, v78, v159
	v_add_f32_e32 v78, v78, v156
	v_add_f32_e32 v78, v78, v157
	v_add_f32_e32 v78, v78, v162
	v_add_f32_e32 v78, v78, v163
	v_add_f32_e32 v78, v78, v160
	v_add_f32_e32 v78, v78, v161
	v_add_f32_e32 v78, v78, v166
	v_add_f32_e32 v78, v78, v167
	v_add_f32_e32 v78, v78, v164
	v_pk_mul_f32 v[110:111], v[50:51], v[50:51]
	v_add_f32_e32 v78, v78, v165
	v_add_f32_e32 v78, v78, v110
	v_add_f32_e32 v78, v78, v111
	v_add_f32_e32 v78, v78, v172
	v_pk_mul_f32 v[104:105], v[38:39], v[38:39]
	v_add_f32_e32 v78, v78, v173
	v_add_f32_e32 v78, v78, v104
	v_pk_mul_f32 v[112:113], v[36:37], v[36:37]
	v_add_f32_e32 v78, v78, v105
	v_add_f32_e32 v78, v78, v112
	v_pk_mul_f32 v[96:97], v[34:35], v[34:35]
	v_add_f32_e32 v78, v78, v113
	v_add_f32_e32 v78, v78, v96
	v_pk_mul_f32 v[108:109], v[32:33], v[32:33]
	v_add_f32_e32 v78, v78, v97
	v_add_f32_e32 v78, v78, v108
	v_pk_mul_f32 v[28:29], v[26:27], v[26:27]
	v_add_f32_e32 v78, v78, v109
	v_add_f32_e32 v28, v78, v28
	v_pk_mul_f32 v[30:31], v[24:25], v[24:25]
	v_add_f32_e32 v28, v28, v29
	v_add_f32_e32 v28, v28, v30
	v_pk_mul_f32 v[0:1], v[22:23], v[22:23]
	v_add_f32_e32 v28, v28, v31
	v_add_f32_e32 v0, v28, v0
	v_pk_mul_f32 v[2:3], v[20:21], v[20:21]
	v_add_f32_e32 v0, v0, v1
	v_add_f32_e32 v0, v0, v2
	v_pk_mul_f32 v[90:91], v[18:19], v[18:19]
	v_add_f32_e32 v0, v0, v3
	v_add_f32_e32 v0, v0, v90
	v_pk_mul_f32 v[92:93], v[16:17], v[16:17]
	v_add_f32_e32 v0, v0, v91
	v_add_f32_e32 v0, v0, v92
	v_pk_mul_f32 v[8:9], v[6:7], v[6:7]
	v_add_f32_e32 v0, v0, v93
	v_add_f32_e32 v0, v0, v8
	v_pk_mul_f32 v[10:11], v[4:5], v[4:5]
	v_add_f32_e32 v0, v0, v9
	v_add_f32_e32 v0, v0, v10
	v_add_f32_e32 v0, v0, v11
	v_add_f32_e32 v0, v0, v116
	v_add_f32_e32 v0, v0, v117
	v_add_f32_e32 v0, v0, v118
	v_add_f32_e32 v2, v0, v119
	ds_bpermute_b32 v3, v244, v2
	v_add_f32_e32 v0, 1.0, v79
	v_add_f32_e32 v1, 1.0, v174
	v_rcp_f32_e32 v0, v0
	v_rcp_f32_e32 v1, v1
	s_waitcnt lgkmcnt(0)
	v_add_f32_e32 v2, v2, v3
	v_fmamk_f32 v2, v2, 0x3c000000, v233
	v_mul_f32_e32 v3, 0x4b800000, v2
	v_cmp_gt_f32_e32 vcc, s8, v2
	v_pk_mul_f32 v[0:1], v[0:1], v[98:99]
	v_lshl_add_u64 v[8:9], v[192:193], 0, v[80:81]
	v_cndmask_b32_e32 v2, v2, v3, vcc
	v_rsq_f32_e32 v10, v2
	v_pk_mul_f32 v[2:3], v[170:171], v[168:169]
	s_waitcnt vmcnt(0)
	v_lshlrev_b32_e32 v30, 16, v114
	v_and_b32_e32 v31, 0xffff0000, v114
	v_mul_f32_e32 v11, 0x45800000, v10
	v_cndmask_b32_e32 v10, v10, v11, vcc
	v_mul_f32_e32 v10, 0x3f24fd5c, v10
	v_pk_mul_f32 v[28:29], v[84:85], v[10:11] op_sel_hi:[1,0]
	s_nop 0
	v_pk_mul_f32 v[28:29], v[64:65], v[28:29]
	v_mul_f32_e32 v65, 0xbfb8aa3b, v31
	v_pk_mul_f32 v[2:3], v[2:3], v[28:29]
	v_pk_mul_f32 v[28:29], v[82:83], v[10:11] op_sel_hi:[1,0]
	v_cvt_pk_bf16_f32 v2, v2, v3
	v_pk_mul_f32 v[28:29], v[66:67], v[28:29]
	v_mul_f32_e32 v11, 0xbfb8aa3b, v30
	v_pk_mul_f32 v[0:1], v[0:1], v[28:29]
	v_exp_f32_e32 v11, v11
	v_cvt_pk_bf16_f32 v3, v0, v1
	global_store_dwordx2 v[8:9], v[2:3], off
	global_load_dwordx4 v[0:3], v[188:189], off offset:32
	s_nop 0
	global_load_dwordx2 v[28:29], v[68:69], off offset:32
	v_exp_f32_e32 v67, v65
	v_lshlrev_b32_e32 v64, 16, v115
	v_add_f32_e32 v11, 1.0, v11
	v_and_b32_e32 v65, 0xffff0000, v115
	v_rcp_f32_e32 v66, v11
	v_add_f32_e32 v11, 1.0, v67
	v_mul_f32_e32 v67, 0xbfb8aa3b, v64
	v_exp_f32_e32 v78, v67
	v_mul_f32_e32 v67, 0xbfb8aa3b, v65
	v_exp_f32_e32 v79, v67
	v_rcp_f32_e32 v67, v11
	v_add_f32_e32 v11, 1.0, v78
	v_rcp_f32_e32 v78, v11
	v_add_f32_e32 v11, 1.0, v79
	v_rcp_f32_e32 v79, v11
	v_pk_mul_f32 v[30:31], v[66:67], v[30:31]
	v_pk_mul_f32 v[66:67], v[76:77], v[10:11] op_sel_hi:[1,0]
	v_pk_mul_f32 v[64:65], v[78:79], v[64:65]
	s_waitcnt vmcnt(1)
	v_pk_mul_f32 v[0:1], v[0:1], v[66:67]
	s_nop 0
	v_pk_mul_f32 v[0:1], v[30:31], v[0:1]
	v_pk_mul_f32 v[30:31], v[74:75], v[10:11] op_sel_hi:[1,0]
	v_cvt_pk_bf16_f32 v0, v0, v1
	v_pk_mul_f32 v[2:3], v[2:3], v[30:31]
	s_nop 0
	v_pk_mul_f32 v[2:3], v[2:3], v[64:65]
	s_waitcnt vmcnt(0)
	v_lshlrev_b32_e32 v64, 16, v28
	v_cvt_pk_bf16_f32 v1, v2, v3
	global_store_dwordx2 v[8:9], v[0:1], off offset:16
	global_load_dwordx4 v[0:3], v[188:189], off offset:64
	s_nop 0
	global_load_dwordx2 v[30:31], v[68:69], off offset:48
	v_and_b32_e32 v65, 0xffff0000, v28
	v_mul_f32_e32 v11, 0xbfb8aa3b, v64
	v_exp_f32_e32 v11, v11
	v_mul_f32_e32 v66, 0xbfb8aa3b, v65
	v_exp_f32_e32 v67, v66
	v_lshlrev_b32_e32 v28, 16, v29
	v_add_f32_e32 v11, 1.0, v11
	v_and_b32_e32 v29, 0xffff0000, v29
	v_rcp_f32_e32 v66, v11
	v_add_f32_e32 v11, 1.0, v67
	v_mul_f32_e32 v67, 0xbfb8aa3b, v28
	v_exp_f32_e32 v74, v67
	v_mul_f32_e32 v67, 0xbfb8aa3b, v29
	v_exp_f32_e32 v75, v67
	v_rcp_f32_e32 v67, v11
	v_add_f32_e32 v11, 1.0, v74
	v_rcp_f32_e32 v74, v11
	v_add_f32_e32 v11, 1.0, v75
	v_rcp_f32_e32 v75, v11
	v_pk_mul_f32 v[64:65], v[66:67], v[64:65]
	v_pk_mul_f32 v[66:67], v[70:71], v[10:11] op_sel_hi:[1,0]
	v_pk_mul_f32 v[58:59], v[58:59], v[10:11] op_sel_hi:[1,0]
	v_pk_mul_f32 v[28:29], v[74:75], v[28:29]
	s_waitcnt vmcnt(1)
	v_pk_mul_f32 v[0:1], v[66:67], v[0:1]
	v_pk_mul_f32 v[2:3], v[58:59], v[2:3]
	v_pk_mul_f32 v[0:1], v[0:1], v[64:65]
	v_pk_mul_f32 v[2:3], v[2:3], v[28:29]
	v_cvt_pk_bf16_f32 v0, v0, v1
	v_cvt_pk_bf16_f32 v1, v2, v3
	global_load_dwordx4 v[128:131], v[188:189], off offset:96
	global_load_dwordx2 v[28:29], v[68:69], off offset:64
	global_store_dwordx2 v[8:9], v[0:1], off offset:32
	s_waitcnt vmcnt(3)
	v_lshlrev_b32_e32 v58, 16, v30
	v_and_b32_e32 v59, 0xffff0000, v30
	v_lshlrev_b32_e32 v30, 16, v31
	v_and_b32_e32 v31, 0xffff0000, v31
	v_mul_f32_e32 v11, 0xbfb8aa3b, v58
	v_mul_f32_e32 v64, 0xbfb8aa3b, v59
	v_mul_f32_e32 v65, 0xbfb8aa3b, v30
	v_mul_f32_e32 v66, 0xbfb8aa3b, v31
	v_exp_f32_e32 v11, v11
	v_exp_f32_e32 v64, v64
	v_exp_f32_e32 v65, v65
	v_exp_f32_e32 v66, v66
	v_add_f32_e32 v11, 1.0, v11
	v_add_f32_e32 v67, 1.0, v64
	v_add_f32_e32 v70, 1.0, v65
	v_add_f32_e32 v71, 1.0, v66
	v_rcp_f32_e32 v64, v11
	v_rcp_f32_e32 v65, v67
	v_rcp_f32_e32 v66, v70
	v_rcp_f32_e32 v67, v71
	v_pk_mul_f32 v[62:63], v[62:63], v[10:11] op_sel_hi:[1,0]
	v_pk_mul_f32 v[56:57], v[56:57], v[10:11] op_sel_hi:[1,0]
	v_pk_mul_f32 v[58:59], v[64:65], v[58:59]
	v_pk_mul_f32 v[30:31], v[66:67], v[30:31]
	s_waitcnt vmcnt(2)
	v_pk_mul_f32 v[0:1], v[62:63], v[128:129]
	v_pk_mul_f32 v[2:3], v[56:57], v[130:131]
	v_pk_mul_f32 v[0:1], v[0:1], v[58:59]
	v_pk_mul_f32 v[2:3], v[2:3], v[30:31]
	v_cvt_pk_bf16_f32 v0, v0, v1
	v_cvt_pk_bf16_f32 v1, v2, v3
	global_load_dwordx4 v[132:135], v[188:189], off offset:128
	global_load_dwordx2 v[30:31], v[68:69], off offset:80
	global_store_dwordx2 v[8:9], v[0:1], off offset:48
	s_waitcnt vmcnt(4)
	v_lshlrev_b32_e32 v56, 16, v28
	v_and_b32_e32 v57, 0xffff0000, v28
	v_lshlrev_b32_e32 v28, 16, v29
	v_and_b32_e32 v29, 0xffff0000, v29
	v_mul_f32_e32 v11, 0xbfb8aa3b, v56
	v_mul_f32_e32 v58, 0xbfb8aa3b, v57
	v_mul_f32_e32 v59, 0xbfb8aa3b, v28
	v_mul_f32_e32 v62, 0xbfb8aa3b, v29
	v_exp_f32_e32 v11, v11
	v_exp_f32_e32 v58, v58
	v_exp_f32_e32 v59, v59
	v_exp_f32_e32 v62, v62
	v_add_f32_e32 v11, 1.0, v11
	v_add_f32_e32 v63, 1.0, v58
	v_add_f32_e32 v64, 1.0, v59
	v_add_f32_e32 v65, 1.0, v62
	v_rcp_f32_e32 v58, v11
	v_rcp_f32_e32 v59, v63
	v_rcp_f32_e32 v62, v64
	v_rcp_f32_e32 v63, v65
	v_pk_mul_f32 v[64:65], v[72:73], v[10:11] op_sel_hi:[1,0]
	v_pk_mul_f32 v[60:61], v[60:61], v[10:11] op_sel_hi:[1,0]
	v_pk_mul_f32 v[56:57], v[58:59], v[56:57]
	v_pk_mul_f32 v[28:29], v[62:63], v[28:29]
	s_waitcnt vmcnt(2)
	v_pk_mul_f32 v[0:1], v[64:65], v[132:133]
	v_pk_mul_f32 v[2:3], v[60:61], v[134:135]
	v_pk_mul_f32 v[0:1], v[0:1], v[56:57]
	v_pk_mul_f32 v[2:3], v[2:3], v[28:29]
	v_cvt_pk_bf16_f32 v0, v0, v1
	v_cvt_pk_bf16_f32 v1, v2, v3
	global_load_dwordx4 v[128:131], v[188:189], off offset:160
	global_load_dwordx2 v[28:29], v[68:69], off offset:96
	global_store_dwordx2 v[8:9], v[0:1], off offset:64
	s_waitcnt vmcnt(4)
	v_lshlrev_b32_e32 v56, 16, v30
	v_and_b32_e32 v57, 0xffff0000, v30
	v_lshlrev_b32_e32 v30, 16, v31
	v_and_b32_e32 v31, 0xffff0000, v31
	v_mul_f32_e32 v11, 0xbfb8aa3b, v56
	v_mul_f32_e32 v58, 0xbfb8aa3b, v57
	v_mul_f32_e32 v59, 0xbfb8aa3b, v30
	v_mul_f32_e32 v60, 0xbfb8aa3b, v31
	v_exp_f32_e32 v11, v11
	v_exp_f32_e32 v58, v58
	v_exp_f32_e32 v59, v59
	v_exp_f32_e32 v60, v60
	v_add_f32_e32 v11, 1.0, v11
	v_add_f32_e32 v61, 1.0, v58
	v_add_f32_e32 v62, 1.0, v59
	v_add_f32_e32 v63, 1.0, v60
	v_rcp_f32_e32 v58, v11
	v_rcp_f32_e32 v59, v61
	v_rcp_f32_e32 v60, v62
	v_rcp_f32_e32 v61, v63
	v_pk_mul_f32 v[54:55], v[54:55], v[10:11] op_sel_hi:[1,0]
	v_pk_mul_f32 v[52:53], v[52:53], v[10:11] op_sel_hi:[1,0]
	v_pk_mul_f32 v[56:57], v[58:59], v[56:57]
	v_pk_mul_f32 v[30:31], v[60:61], v[30:31]
	s_waitcnt vmcnt(2)
	v_pk_mul_f32 v[0:1], v[54:55], v[128:129]
	v_pk_mul_f32 v[2:3], v[52:53], v[130:131]
	v_pk_mul_f32 v[0:1], v[0:1], v[56:57]
	v_pk_mul_f32 v[2:3], v[2:3], v[30:31]
	v_cvt_pk_bf16_f32 v0, v0, v1
	v_cvt_pk_bf16_f32 v1, v2, v3
	global_load_dwordx4 v[132:135], v[188:189], off offset:192
	global_load_dwordx2 v[30:31], v[68:69], off offset:112
	global_store_dwordx2 v[8:9], v[0:1], off offset:80
	s_waitcnt vmcnt(4)
	v_lshlrev_b32_e32 v52, 16, v28
	v_and_b32_e32 v53, 0xffff0000, v28
	v_lshlrev_b32_e32 v28, 16, v29
	v_and_b32_e32 v29, 0xffff0000, v29
	v_mul_f32_e32 v11, 0xbfb8aa3b, v52
	v_mul_f32_e32 v54, 0xbfb8aa3b, v53
	v_mul_f32_e32 v55, 0xbfb8aa3b, v28
	v_mul_f32_e32 v56, 0xbfb8aa3b, v29
	v_exp_f32_e32 v11, v11
	v_exp_f32_e32 v54, v54
	v_exp_f32_e32 v55, v55
	v_exp_f32_e32 v56, v56
	v_add_f32_e32 v11, 1.0, v11
	v_add_f32_e32 v57, 1.0, v54
	v_add_f32_e32 v58, 1.0, v55
	v_add_f32_e32 v59, 1.0, v56
	v_rcp_f32_e32 v54, v11
	v_rcp_f32_e32 v55, v57
	v_rcp_f32_e32 v56, v58
	v_rcp_f32_e32 v57, v59
	v_pk_mul_f32 v[48:49], v[48:49], v[10:11] op_sel_hi:[1,0]
	v_pk_mul_f32 v[42:43], v[42:43], v[10:11] op_sel_hi:[1,0]
	v_pk_mul_f32 v[52:53], v[54:55], v[52:53]
	v_pk_mul_f32 v[28:29], v[56:57], v[28:29]
	s_waitcnt vmcnt(2)
	v_pk_mul_f32 v[0:1], v[48:49], v[132:133]
	v_pk_mul_f32 v[2:3], v[42:43], v[134:135]
	v_pk_mul_f32 v[0:1], v[0:1], v[52:53]
	v_pk_mul_f32 v[2:3], v[2:3], v[28:29]
	v_cvt_pk_bf16_f32 v0, v0, v1
	v_cvt_pk_bf16_f32 v1, v2, v3
	global_load_dwordx4 v[128:131], v[188:189], off offset:224
	global_load_dwordx2 v[28:29], v[68:69], off offset:128
	global_store_dwordx2 v[8:9], v[0:1], off offset:96
	s_waitcnt vmcnt(4)
	v_lshlrev_b32_e32 v42, 16, v30
	v_and_b32_e32 v43, 0xffff0000, v30
	v_lshlrev_b32_e32 v30, 16, v31
	v_and_b32_e32 v31, 0xffff0000, v31
	v_mul_f32_e32 v11, 0xbfb8aa3b, v42
	v_mul_f32_e32 v48, 0xbfb8aa3b, v43
	v_mul_f32_e32 v49, 0xbfb8aa3b, v30
	v_mul_f32_e32 v52, 0xbfb8aa3b, v31
	v_exp_f32_e32 v11, v11
	v_exp_f32_e32 v48, v48
	v_exp_f32_e32 v49, v49
	v_exp_f32_e32 v52, v52
	v_add_f32_e32 v11, 1.0, v11
	v_add_f32_e32 v53, 1.0, v48
	v_add_f32_e32 v54, 1.0, v49
	v_add_f32_e32 v55, 1.0, v52
	v_rcp_f32_e32 v48, v11
	v_rcp_f32_e32 v49, v53
	v_rcp_f32_e32 v52, v54
	v_rcp_f32_e32 v53, v55
	v_pk_mul_f32 v[44:45], v[44:45], v[10:11] op_sel_hi:[1,0]
	v_pk_mul_f32 v[40:41], v[40:41], v[10:11] op_sel_hi:[1,0]
	v_pk_mul_f32 v[42:43], v[48:49], v[42:43]
	v_pk_mul_f32 v[30:31], v[52:53], v[30:31]
	s_waitcnt vmcnt(2)
	v_pk_mul_f32 v[0:1], v[44:45], v[128:129]
	v_pk_mul_f32 v[2:3], v[40:41], v[130:131]
	v_pk_mul_f32 v[0:1], v[0:1], v[42:43]
	v_pk_mul_f32 v[2:3], v[2:3], v[30:31]
	v_cvt_pk_bf16_f32 v0, v0, v1
	v_cvt_pk_bf16_f32 v1, v2, v3
	global_load_dwordx4 v[132:135], v[188:189], off offset:256
	global_load_dwordx2 v[30:31], v[68:69], off offset:144
	global_store_dwordx2 v[8:9], v[0:1], off offset:112
	s_waitcnt vmcnt(4)
	v_lshlrev_b32_e32 v40, 16, v28
	v_and_b32_e32 v41, 0xffff0000, v28
	v_lshlrev_b32_e32 v28, 16, v29
	v_and_b32_e32 v29, 0xffff0000, v29
	v_mul_f32_e32 v11, 0xbfb8aa3b, v40
	v_mul_f32_e32 v42, 0xbfb8aa3b, v41
	v_mul_f32_e32 v43, 0xbfb8aa3b, v28
	v_mul_f32_e32 v44, 0xbfb8aa3b, v29
	v_exp_f32_e32 v11, v11
	v_exp_f32_e32 v42, v42
	v_exp_f32_e32 v43, v43
	v_exp_f32_e32 v44, v44
	v_add_f32_e32 v11, 1.0, v11
	v_add_f32_e32 v45, 1.0, v42
	v_add_f32_e32 v48, 1.0, v43
	v_add_f32_e32 v49, 1.0, v44
	v_rcp_f32_e32 v42, v11
	v_rcp_f32_e32 v43, v45
	v_rcp_f32_e32 v44, v48
	v_rcp_f32_e32 v45, v49
	v_pk_mul_f32 v[48:49], v[50:51], v[10:11] op_sel_hi:[1,0]
	v_pk_mul_f32 v[46:47], v[46:47], v[10:11] op_sel_hi:[1,0]
	v_pk_mul_f32 v[40:41], v[42:43], v[40:41]
	v_pk_mul_f32 v[28:29], v[44:45], v[28:29]
	s_waitcnt vmcnt(2)
	v_pk_mul_f32 v[0:1], v[48:49], v[132:133]
	v_pk_mul_f32 v[2:3], v[46:47], v[134:135]
	v_pk_mul_f32 v[0:1], v[0:1], v[40:41]
	v_pk_mul_f32 v[2:3], v[2:3], v[28:29]
	v_cvt_pk_bf16_f32 v0, v0, v1
	v_cvt_pk_bf16_f32 v1, v2, v3
	global_load_dwordx4 v[128:131], v[188:189], off offset:288
	global_load_dwordx2 v[28:29], v[68:69], off offset:160
	global_store_dwordx2 v[8:9], v[0:1], off offset:128
	s_waitcnt vmcnt(4)
	v_lshlrev_b32_e32 v40, 16, v30
	v_and_b32_e32 v41, 0xffff0000, v30
	v_lshlrev_b32_e32 v30, 16, v31
	v_and_b32_e32 v31, 0xffff0000, v31
	v_mul_f32_e32 v11, 0xbfb8aa3b, v40
	v_mul_f32_e32 v42, 0xbfb8aa3b, v41
	v_mul_f32_e32 v43, 0xbfb8aa3b, v30
	v_mul_f32_e32 v44, 0xbfb8aa3b, v31
	v_exp_f32_e32 v11, v11
	v_exp_f32_e32 v42, v42
	v_exp_f32_e32 v43, v43
	v_exp_f32_e32 v44, v44
	v_add_f32_e32 v11, 1.0, v11
	v_add_f32_e32 v45, 1.0, v42
	v_add_f32_e32 v46, 1.0, v43
	v_add_f32_e32 v47, 1.0, v44
	v_rcp_f32_e32 v42, v11
	v_rcp_f32_e32 v43, v45
	v_rcp_f32_e32 v44, v46
	v_rcp_f32_e32 v45, v47
	v_pk_mul_f32 v[38:39], v[38:39], v[10:11] op_sel_hi:[1,0]
	v_pk_mul_f32 v[36:37], v[36:37], v[10:11] op_sel_hi:[1,0]
	v_pk_mul_f32 v[40:41], v[42:43], v[40:41]
	v_pk_mul_f32 v[30:31], v[44:45], v[30:31]
	s_waitcnt vmcnt(2)
	v_pk_mul_f32 v[0:1], v[38:39], v[128:129]
	v_pk_mul_f32 v[2:3], v[36:37], v[130:131]
	v_pk_mul_f32 v[0:1], v[0:1], v[40:41]
	v_pk_mul_f32 v[2:3], v[2:3], v[30:31]
	v_cvt_pk_bf16_f32 v0, v0, v1
	v_cvt_pk_bf16_f32 v1, v2, v3
	global_load_dwordx4 v[132:135], v[188:189], off offset:320
	global_load_dwordx2 v[30:31], v[68:69], off offset:176
	global_store_dwordx2 v[8:9], v[0:1], off offset:144
	s_waitcnt vmcnt(4)
	v_lshlrev_b32_e32 v36, 16, v28
	v_and_b32_e32 v37, 0xffff0000, v28
	v_lshlrev_b32_e32 v28, 16, v29
	v_and_b32_e32 v29, 0xffff0000, v29
	v_mul_f32_e32 v11, 0xbfb8aa3b, v36
	v_mul_f32_e32 v38, 0xbfb8aa3b, v37
	v_mul_f32_e32 v39, 0xbfb8aa3b, v28
	v_mul_f32_e32 v40, 0xbfb8aa3b, v29
	v_exp_f32_e32 v11, v11
	v_exp_f32_e32 v38, v38
	v_exp_f32_e32 v39, v39
	v_exp_f32_e32 v40, v40
	v_add_f32_e32 v11, 1.0, v11
	v_add_f32_e32 v41, 1.0, v38
	v_add_f32_e32 v42, 1.0, v39
	v_add_f32_e32 v43, 1.0, v40
	v_rcp_f32_e32 v38, v11
	v_rcp_f32_e32 v39, v41
	v_rcp_f32_e32 v40, v42
	v_rcp_f32_e32 v41, v43
	v_pk_mul_f32 v[34:35], v[34:35], v[10:11] op_sel_hi:[1,0]
	v_pk_mul_f32 v[32:33], v[32:33], v[10:11] op_sel_hi:[1,0]
	v_pk_mul_f32 v[36:37], v[38:39], v[36:37]
	v_pk_mul_f32 v[28:29], v[40:41], v[28:29]
	s_waitcnt vmcnt(2)
	v_pk_mul_f32 v[0:1], v[34:35], v[132:133]
	v_pk_mul_f32 v[2:3], v[32:33], v[134:135]
	v_pk_mul_f32 v[0:1], v[0:1], v[36:37]
	v_pk_mul_f32 v[2:3], v[2:3], v[28:29]
	v_cvt_pk_bf16_f32 v0, v0, v1
	v_cvt_pk_bf16_f32 v1, v2, v3
	global_load_dwordx4 v[128:131], v[188:189], off offset:352
	global_load_dwordx2 v[28:29], v[68:69], off offset:192
	global_store_dwordx2 v[8:9], v[0:1], off offset:160
	s_waitcnt vmcnt(4)
	v_lshlrev_b32_e32 v32, 16, v30
	v_and_b32_e32 v33, 0xffff0000, v30
	v_lshlrev_b32_e32 v30, 16, v31
	v_and_b32_e32 v31, 0xffff0000, v31
	v_mul_f32_e32 v11, 0xbfb8aa3b, v32
	v_mul_f32_e32 v34, 0xbfb8aa3b, v33
	v_mul_f32_e32 v35, 0xbfb8aa3b, v30
	v_mul_f32_e32 v36, 0xbfb8aa3b, v31
	v_exp_f32_e32 v11, v11
	v_exp_f32_e32 v34, v34
	v_exp_f32_e32 v35, v35
	v_exp_f32_e32 v36, v36
	v_add_f32_e32 v11, 1.0, v11
	v_add_f32_e32 v37, 1.0, v34
	v_add_f32_e32 v38, 1.0, v35
	v_add_f32_e32 v39, 1.0, v36
	v_rcp_f32_e32 v34, v11
	v_rcp_f32_e32 v35, v37
	v_rcp_f32_e32 v36, v38
	v_rcp_f32_e32 v37, v39
	v_pk_mul_f32 v[26:27], v[26:27], v[10:11] op_sel_hi:[1,0]
	v_pk_mul_f32 v[24:25], v[24:25], v[10:11] op_sel_hi:[1,0]
	v_pk_mul_f32 v[32:33], v[34:35], v[32:33]
	v_pk_mul_f32 v[30:31], v[36:37], v[30:31]
	s_waitcnt vmcnt(2)
	v_pk_mul_f32 v[0:1], v[26:27], v[128:129]
	v_pk_mul_f32 v[2:3], v[24:25], v[130:131]
	v_pk_mul_f32 v[0:1], v[0:1], v[32:33]
	v_pk_mul_f32 v[2:3], v[2:3], v[30:31]
	v_cvt_pk_bf16_f32 v0, v0, v1
	v_cvt_pk_bf16_f32 v1, v2, v3
	global_load_dwordx4 v[132:135], v[188:189], off offset:384
	global_load_dwordx2 v[24:25], v[68:69], off offset:208
	global_store_dwordx2 v[8:9], v[0:1], off offset:176
	s_waitcnt vmcnt(4)
	v_lshlrev_b32_e32 v26, 16, v28
	v_and_b32_e32 v27, 0xffff0000, v28
	v_lshlrev_b32_e32 v28, 16, v29
	v_and_b32_e32 v29, 0xffff0000, v29
	v_mul_f32_e32 v11, 0xbfb8aa3b, v26
	v_mul_f32_e32 v30, 0xbfb8aa3b, v27
	v_mul_f32_e32 v31, 0xbfb8aa3b, v28
	v_mul_f32_e32 v32, 0xbfb8aa3b, v29
	v_exp_f32_e32 v11, v11
	v_exp_f32_e32 v30, v30
	v_exp_f32_e32 v31, v31
	v_exp_f32_e32 v32, v32
	v_add_f32_e32 v11, 1.0, v11
	v_add_f32_e32 v33, 1.0, v30
	v_add_f32_e32 v34, 1.0, v31
	v_add_f32_e32 v35, 1.0, v32
	v_rcp_f32_e32 v30, v11
	v_rcp_f32_e32 v31, v33
	v_rcp_f32_e32 v32, v34
	v_rcp_f32_e32 v33, v35
	v_pk_mul_f32 v[22:23], v[22:23], v[10:11] op_sel_hi:[1,0]
	v_pk_mul_f32 v[20:21], v[20:21], v[10:11] op_sel_hi:[1,0]
	v_pk_mul_f32 v[26:27], v[30:31], v[26:27]
	v_pk_mul_f32 v[28:29], v[32:33], v[28:29]
	s_waitcnt vmcnt(2)
	v_pk_mul_f32 v[0:1], v[22:23], v[132:133]
	v_pk_mul_f32 v[2:3], v[20:21], v[134:135]
	v_pk_mul_f32 v[0:1], v[0:1], v[26:27]
	v_pk_mul_f32 v[2:3], v[2:3], v[28:29]
	v_cvt_pk_bf16_f32 v0, v0, v1
	v_cvt_pk_bf16_f32 v1, v2, v3
	global_load_dwordx4 v[128:131], v[188:189], off offset:416
	global_load_dwordx2 v[20:21], v[68:69], off offset:224
	global_store_dwordx2 v[8:9], v[0:1], off offset:192
	s_waitcnt vmcnt(4)
	v_lshlrev_b32_e32 v22, 16, v24
	v_and_b32_e32 v23, 0xffff0000, v24
	v_lshlrev_b32_e32 v24, 16, v25
	v_and_b32_e32 v25, 0xffff0000, v25
	v_mul_f32_e32 v11, 0xbfb8aa3b, v22
	v_mul_f32_e32 v26, 0xbfb8aa3b, v23
	v_mul_f32_e32 v27, 0xbfb8aa3b, v24
	v_mul_f32_e32 v28, 0xbfb8aa3b, v25
	v_exp_f32_e32 v11, v11
	v_exp_f32_e32 v26, v26
	v_exp_f32_e32 v27, v27
	v_exp_f32_e32 v28, v28
	v_add_f32_e32 v11, 1.0, v11
	v_add_f32_e32 v29, 1.0, v26
	v_add_f32_e32 v30, 1.0, v27
	v_add_f32_e32 v31, 1.0, v28
	v_rcp_f32_e32 v26, v11
	v_rcp_f32_e32 v27, v29
	v_rcp_f32_e32 v28, v30
	v_rcp_f32_e32 v29, v31
	v_pk_mul_f32 v[18:19], v[18:19], v[10:11] op_sel_hi:[1,0]
	v_pk_mul_f32 v[16:17], v[16:17], v[10:11] op_sel_hi:[1,0]
	v_pk_mul_f32 v[22:23], v[26:27], v[22:23]
	v_pk_mul_f32 v[24:25], v[28:29], v[24:25]
	s_waitcnt vmcnt(2)
	v_pk_mul_f32 v[0:1], v[18:19], v[128:129]
	v_pk_mul_f32 v[2:3], v[16:17], v[130:131]
	v_pk_mul_f32 v[0:1], v[0:1], v[22:23]
	v_pk_mul_f32 v[2:3], v[2:3], v[24:25]
	v_cvt_pk_bf16_f32 v0, v0, v1
	v_cvt_pk_bf16_f32 v1, v2, v3
	global_load_dwordx4 v[132:135], v[188:189], off offset:448
	global_load_dwordx2 v[16:17], v[68:69], off offset:240
	global_store_dwordx2 v[8:9], v[0:1], off offset:208
	s_waitcnt vmcnt(4)
	v_lshlrev_b32_e32 v18, 16, v20
	v_and_b32_e32 v19, 0xffff0000, v20
	v_lshlrev_b32_e32 v20, 16, v21
	v_and_b32_e32 v21, 0xffff0000, v21
	v_mul_f32_e32 v11, 0xbfb8aa3b, v18
	v_mul_f32_e32 v22, 0xbfb8aa3b, v19
	v_mul_f32_e32 v23, 0xbfb8aa3b, v20
	v_mul_f32_e32 v24, 0xbfb8aa3b, v21
	v_exp_f32_e32 v11, v11
	v_exp_f32_e32 v22, v22
	v_exp_f32_e32 v23, v23
	v_exp_f32_e32 v24, v24
	v_add_f32_e32 v11, 1.0, v11
	v_add_f32_e32 v25, 1.0, v22
	v_add_f32_e32 v26, 1.0, v23
	v_add_f32_e32 v27, 1.0, v24
	v_rcp_f32_e32 v22, v11
	v_rcp_f32_e32 v23, v25
	v_rcp_f32_e32 v24, v26
	v_rcp_f32_e32 v25, v27
	v_pk_mul_f32 v[6:7], v[6:7], v[10:11] op_sel_hi:[1,0]
	v_pk_mul_f32 v[4:5], v[4:5], v[10:11] op_sel_hi:[1,0]
	v_pk_mul_f32 v[18:19], v[22:23], v[18:19]
	v_pk_mul_f32 v[20:21], v[24:25], v[20:21]
	s_waitcnt vmcnt(2)
	v_pk_mul_f32 v[0:1], v[6:7], v[132:133]
	v_pk_mul_f32 v[2:3], v[4:5], v[134:135]
	v_pk_mul_f32 v[0:1], v[0:1], v[18:19]
	v_pk_mul_f32 v[2:3], v[2:3], v[20:21]
	v_cvt_pk_bf16_f32 v0, v0, v1
	v_cvt_pk_bf16_f32 v1, v2, v3
	global_store_dwordx2 v[8:9], v[0:1], off offset:224
	global_load_dwordx4 v[0:3], v[188:189], off offset:480
	s_waitcnt vmcnt(2)
	v_lshlrev_b32_e32 v4, 16, v16
	v_and_b32_e32 v5, 0xffff0000, v16
	v_lshlrev_b32_e32 v6, 16, v17
	v_and_b32_e32 v7, 0xffff0000, v17
	v_mul_f32_e32 v11, 0xbfb8aa3b, v4
	v_mul_f32_e32 v16, 0xbfb8aa3b, v5
	v_mul_f32_e32 v17, 0xbfb8aa3b, v6
	v_mul_f32_e32 v18, 0xbfb8aa3b, v7
	v_exp_f32_e32 v11, v11
	v_exp_f32_e32 v16, v16
	v_exp_f32_e32 v17, v17
	v_exp_f32_e32 v18, v18
	v_add_f32_e32 v11, 1.0, v11
	v_add_f32_e32 v19, 1.0, v16
	v_add_f32_e32 v20, 1.0, v17
	v_add_f32_e32 v21, 1.0, v18
	v_rcp_f32_e32 v16, v11
	v_rcp_f32_e32 v17, v19
	v_rcp_f32_e32 v18, v20
	v_rcp_f32_e32 v19, v21
	v_pk_mul_f32 v[12:13], v[12:13], v[10:11] op_sel_hi:[1,0]
	v_pk_mul_f32 v[10:11], v[14:15], v[10:11] op_sel_hi:[1,0]
	v_pk_mul_f32 v[4:5], v[16:17], v[4:5]
	v_pk_mul_f32 v[6:7], v[18:19], v[6:7]
	s_waitcnt vmcnt(0)
	v_pk_mul_f32 v[0:1], v[12:13], v[0:1]
	v_pk_mul_f32 v[2:3], v[10:11], v[2:3]
	v_pk_mul_f32 v[0:1], v[0:1], v[4:5]
	v_pk_mul_f32 v[2:3], v[2:3], v[6:7]
	v_cvt_pk_bf16_f32 v0, v0, v1
	v_cvt_pk_bf16_f32 v1, v2, v3
	global_store_dwordx2 v[8:9], v[0:1], off offset:240
